# grid barrier: every workgroup issues its acquire-side buffer_inv sc1 at arrival (behind the arrival atomic) so it completes while waiting, not after the release
# baseline (speedup 1.0000x reference)
.LBB0_25:
	s_or_b64 exec, exec, s[10:11]
	buffer_inv sc1
	v_cvt_f32_u32_e32 v5, v3
	s_waitcnt vmcnt(1)
	v_readfirstlane_b32 s8, v4
	v_sub_u32_e32 v4, 0, v3
	v_rcp_iflag_f32_e32 v5, v5
	v_add_u32_e32 v6, s8, v2
	v_mul_f32_e32 v5, 0x4f7ffffe, v5
	v_cvt_u32_f32_e32 v5, v5
	v_mul_lo_u32 v2, v4, v5
	v_mul_hi_u32 v2, v5, v2
	v_add_u32_e32 v2, v5, v2
	v_mul_hi_u32 v2, v6, v2
	v_mul_lo_u32 v4, v2, v3
	v_sub_u32_e32 v4, v6, v4
	v_add_u32_e32 v5, 1, v2
	v_cmp_ge_u32_e32 vcc, v4, v3
	s_nop 1
	v_cndmask_b32_e32 v2, v2, v5, vcc
	v_sub_u32_e32 v5, v4, v3
	v_cndmask_b32_e32 v4, v4, v5, vcc
	v_add_u32_e32 v5, 1, v2
	v_cmp_ge_u32_e32 vcc, v4, v3
	v_add_u32_e32 v4, 1, v6
	s_nop 0
	v_cndmask_b32_e32 v2, v2, v5, vcc
	v_mul_lo_u32 v5, v3, v2
	v_add_u32_e32 v3, v5, v3
	v_cmp_ne_u32_e32 vcc, v4, v3
	s_and_saveexec_b64 s[8:9], vcc
	s_xor_b64 s[8:9], exec, s[8:9]
	s_cbranch_execz .LBB0_39
	s_waitcnt lgkmcnt(0)
	v_mov_b32_e32 v1, 0x2000
	global_load_dword v1, v1, s[2:3] offset:1024 sc1
	s_add_u32 s14, s2, 0x2400
	s_addc_u32 s15, s3, 0
	s_waitcnt vmcnt(0)
	v_cmp_eq_u32_e32 vcc, v1, v2
	s_and_saveexec_b64 s[10:11], vcc
	s_cbranch_execz .LBB0_38
	s_add_u32 s12, s62, 0x1e800600
	s_addc_u32 s13, s63, 0
	s_mov_b32 s26, 1
	s_mov_b64 s[16:17], 0
	v_mov_b32_e32 v1, 0
	s_branch .LBB0_29

.LBB0_38:
	s_or_b64 exec, exec, s[10:11]
	s_waitcnt vmcnt(0)
	s_waitcnt vmcnt(0)

.LBB0_144:
	s_or_b64 exec, exec, s[12:13]
	buffer_inv sc1
	v_cvt_f32_u32_e32 v5, v3
	s_waitcnt vmcnt(1)
	v_readfirstlane_b32 s10, v4
	s_add_u32 s8, s8, 0x2400
	s_addc_u32 s9, s9, 0
	v_rcp_iflag_f32_e32 v5, v5
	v_add_u32_e32 v6, s10, v2
	v_mul_f32_e32 v4, 0x4f7ffffe, v5
	v_cvt_u32_f32_e32 v4, v4
	v_sub_u32_e32 v5, 0, v3
	v_mul_lo_u32 v2, v5, v4
	v_mul_hi_u32 v2, v4, v2
	v_add_u32_e32 v2, v4, v2
	v_mul_hi_u32 v2, v6, v2
	v_mul_lo_u32 v4, v2, v3
	v_sub_u32_e32 v4, v6, v4
	v_add_u32_e32 v5, 1, v2
	v_cmp_ge_u32_e32 vcc, v4, v3
	s_nop 1
	v_cndmask_b32_e32 v2, v2, v5, vcc
	v_sub_u32_e32 v5, v4, v3
	v_cndmask_b32_e32 v4, v4, v5, vcc
	v_add_u32_e32 v5, 1, v2
	v_cmp_ge_u32_e32 vcc, v4, v3
	v_add_u32_e32 v4, 1, v6
	s_nop 0
	v_cndmask_b32_e32 v2, v2, v5, vcc
	v_mul_lo_u32 v5, v3, v2
	v_add_u32_e32 v3, v5, v3
	v_cmp_ne_u32_e32 vcc, v4, v3
	s_and_saveexec_b64 s[10:11], vcc
	s_xor_b64 s[10:11], exec, s[10:11]
	s_cbranch_execz .LBB0_158
	s_waitcnt lgkmcnt(0)
	v_mov_b32_e32 v1, 0
	global_load_dword v3, v1, s[8:9] sc1
	s_waitcnt vmcnt(0)
	v_cmp_eq_u32_e32 vcc, v3, v2
	s_and_saveexec_b64 s[12:13], vcc
	s_cbranch_execz .LBB0_157
	s_mov_b32 s24, 1
	s_mov_b64 s[14:15], 0
	s_branch .LBB0_148

.LBB0_157:
	s_or_b64 exec, exec, s[12:13]
	s_waitcnt vmcnt(0)
	s_waitcnt vmcnt(0)

.LBB0_396:
	s_or_b64 exec, exec, s[10:11]
	buffer_inv sc1
	v_cvt_f32_u32_e32 v5, v3
	s_waitcnt vmcnt(1)
	v_readfirstlane_b32 s8, v4
	s_add_u32 s4, s4, 0x2400
	s_addc_u32 s5, s5, 0
	v_rcp_iflag_f32_e32 v5, v5
	v_add_u32_e32 v6, s8, v2
	v_mul_f32_e32 v4, 0x4f7ffffe, v5
	v_cvt_u32_f32_e32 v4, v4
	v_sub_u32_e32 v5, 0, v3
	v_mul_lo_u32 v2, v5, v4
	v_mul_hi_u32 v2, v4, v2
	v_add_u32_e32 v2, v4, v2
	v_mul_hi_u32 v2, v6, v2
	v_mul_lo_u32 v4, v2, v3
	v_sub_u32_e32 v4, v6, v4
	v_add_u32_e32 v5, 1, v2
	v_cmp_ge_u32_e32 vcc, v4, v3
	s_nop 1
	v_cndmask_b32_e32 v2, v2, v5, vcc
	v_sub_u32_e32 v5, v4, v3
	v_cndmask_b32_e32 v4, v4, v5, vcc
	v_add_u32_e32 v5, 1, v2
	v_cmp_ge_u32_e32 vcc, v4, v3
	v_add_u32_e32 v4, 1, v6
	s_nop 0
	v_cndmask_b32_e32 v2, v2, v5, vcc
	v_mul_lo_u32 v5, v3, v2
	v_add_u32_e32 v3, v5, v3
	v_cmp_ne_u32_e32 vcc, v4, v3
	s_and_saveexec_b64 s[8:9], vcc
	s_xor_b64 s[8:9], exec, s[8:9]
	s_cbranch_execz .LBB0_410
	s_waitcnt lgkmcnt(0)
	v_mov_b32_e32 v1, 0
	global_load_dword v3, v1, s[4:5] sc1
	s_waitcnt vmcnt(0)
	v_cmp_eq_u32_e32 vcc, v3, v2
	s_and_saveexec_b64 s[10:11], vcc
	s_cbranch_execz .LBB0_409
	s_mov_b32 s22, 1
	s_mov_b64 s[12:13], 0
	s_branch .LBB0_400

.LBB0_534:
	s_or_b64 exec, exec, s[6:7]
	buffer_inv sc1
	v_cvt_f32_u32_e32 v5, v3
	s_waitcnt vmcnt(1)
	v_readfirstlane_b32 s4, v4
	v_sub_u32_e32 v4, 0, v3
	v_rcp_iflag_f32_e32 v5, v5
	v_add_u32_e32 v6, s4, v2
	v_mul_f32_e32 v5, 0x4f7ffffe, v5
	v_cvt_u32_f32_e32 v5, v5
	v_mul_lo_u32 v2, v4, v5
	v_mul_hi_u32 v2, v5, v2
	v_add_u32_e32 v2, v5, v2
	v_mul_hi_u32 v2, v6, v2
	v_mul_lo_u32 v4, v2, v3
	v_sub_u32_e32 v4, v6, v4
	v_add_u32_e32 v5, 1, v2
	v_cmp_ge_u32_e32 vcc, v4, v3
	s_nop 1
	v_cndmask_b32_e32 v2, v2, v5, vcc
	v_sub_u32_e32 v5, v4, v3
	v_cndmask_b32_e32 v4, v4, v5, vcc
	v_add_u32_e32 v5, 1, v2
	v_cmp_ge_u32_e32 vcc, v4, v3
	v_add_u32_e32 v4, 1, v6
	s_nop 0
	v_cndmask_b32_e32 v2, v2, v5, vcc
	v_mul_lo_u32 v5, v3, v2
	v_add_u32_e32 v3, v5, v3
	v_cmp_ne_u32_e32 vcc, v4, v3
	s_and_saveexec_b64 s[4:5], vcc
	s_xor_b64 s[4:5], exec, s[4:5]
	s_cbranch_execz .LBB0_548
	s_waitcnt lgkmcnt(0)
	v_mov_b32_e32 v1, 0x2000
	global_load_dword v1, v1, s[2:3] offset:1024 sc1
	s_add_u32 s10, s2, 0x2400
	s_addc_u32 s11, s3, 0
	s_waitcnt vmcnt(0)
	v_cmp_eq_u32_e32 vcc, v1, v2
	s_and_saveexec_b64 s[6:7], vcc
	s_cbranch_execz .LBB0_547
	s_add_u32 s8, s62, 0x1e800600
	s_addc_u32 s9, s63, 0
	s_mov_b32 s22, 1
	s_mov_b64 s[12:13], 0
	v_mov_b32_e32 v1, 0
	s_branch .LBB0_538

.LBB0_547:
	s_or_b64 exec, exec, s[6:7]
	s_waitcnt vmcnt(0)
	s_waitcnt vmcnt(0)

.LBB0_681:
	s_or_b64 exec, exec, s[8:9]
	buffer_inv sc1
	v_cvt_f32_u32_e32 v5, v3
	s_waitcnt vmcnt(1)
	v_readfirstlane_b32 s6, v4
	v_sub_u32_e32 v4, 0, v3
	v_rcp_iflag_f32_e32 v5, v5
	v_add_u32_e32 v6, s6, v2
	v_mul_f32_e32 v5, 0x4f7ffffe, v5
	v_cvt_u32_f32_e32 v5, v5
	v_mul_lo_u32 v2, v4, v5
	v_mul_hi_u32 v2, v5, v2
	v_add_u32_e32 v2, v5, v2
	v_mul_hi_u32 v2, v6, v2
	v_mul_lo_u32 v4, v2, v3
	v_sub_u32_e32 v4, v6, v4
	v_add_u32_e32 v5, 1, v2
	v_cmp_ge_u32_e32 vcc, v4, v3
	s_nop 1
	v_cndmask_b32_e32 v2, v2, v5, vcc
	v_sub_u32_e32 v5, v4, v3
	v_cndmask_b32_e32 v4, v4, v5, vcc
	v_add_u32_e32 v5, 1, v2
	v_cmp_ge_u32_e32 vcc, v4, v3
	v_add_u32_e32 v4, 1, v6
	s_nop 0
	v_cndmask_b32_e32 v2, v2, v5, vcc
	v_mul_lo_u32 v5, v3, v2
	v_add_u32_e32 v3, v5, v3
	v_cmp_ne_u32_e32 vcc, v4, v3
	s_and_saveexec_b64 s[6:7], vcc
	s_xor_b64 s[6:7], exec, s[6:7]
	s_cbranch_execz .LBB0_695
	s_waitcnt lgkmcnt(0)
	v_mov_b32_e32 v1, 0x2000
	global_load_dword v1, v1, s[4:5] offset:1024 sc1
	s_add_u32 s12, s4, 0x2400
	s_addc_u32 s13, s5, 0
	s_waitcnt vmcnt(0)
	v_cmp_eq_u32_e32 vcc, v1, v2
	s_and_saveexec_b64 s[8:9], vcc
	s_cbranch_execz .LBB0_694
	s_add_u32 s10, s62, 0x1e800600
	s_addc_u32 s11, s63, 0
	s_mov_b32 s24, 1
	s_mov_b64 s[14:15], 0
	v_mov_b32_e32 v1, 0
	s_branch .LBB0_685

.LBB0_694:
	s_or_b64 exec, exec, s[8:9]
	s_waitcnt vmcnt(0)
	s_waitcnt vmcnt(0)

.LBB0_776:
	s_or_b64 exec, exec, s[8:9]
	buffer_inv sc1
	v_cvt_f32_u32_e32 v5, v3
	s_waitcnt vmcnt(1)
	v_readfirstlane_b32 s4, v4
	v_sub_u32_e32 v4, 0, v3
	v_rcp_iflag_f32_e32 v5, v5
	v_add_u32_e32 v6, s4, v2
	v_mul_f32_e32 v5, 0x4f7ffffe, v5
	v_cvt_u32_f32_e32 v5, v5
	v_mul_lo_u32 v2, v4, v5
	v_mul_hi_u32 v2, v5, v2
	v_add_u32_e32 v2, v5, v2
	v_mul_hi_u32 v2, v6, v2
	v_mul_lo_u32 v4, v2, v3
	v_sub_u32_e32 v4, v6, v4
	v_add_u32_e32 v5, 1, v2
	v_cmp_ge_u32_e32 vcc, v4, v3
	s_nop 1
	v_cndmask_b32_e32 v2, v2, v5, vcc
	v_sub_u32_e32 v5, v4, v3
	v_cndmask_b32_e32 v4, v4, v5, vcc
	v_add_u32_e32 v5, 1, v2
	v_cmp_ge_u32_e32 vcc, v4, v3
	v_add_u32_e32 v4, 1, v6
	s_nop 0
	v_cndmask_b32_e32 v2, v2, v5, vcc
	v_mul_lo_u32 v5, v3, v2
	v_add_u32_e32 v3, v5, v3
	v_cmp_ne_u32_e32 vcc, v4, v3
	s_and_saveexec_b64 s[4:5], vcc
	s_xor_b64 s[4:5], exec, s[4:5]
	s_cbranch_execz .LBB0_790
	s_waitcnt lgkmcnt(0)
	v_mov_b32_e32 v1, 0x2000
	global_load_dword v1, v1, s[2:3] offset:1024 sc1
	s_add_u32 s12, s2, 0x2400
	s_addc_u32 s13, s3, 0
	s_waitcnt vmcnt(0)
	v_cmp_eq_u32_e32 vcc, v1, v2
	s_and_saveexec_b64 s[8:9], vcc
	s_cbranch_execz .LBB0_789
	s_add_u32 s10, s62, 0x1e800600
	s_addc_u32 s11, s63, 0
	s_mov_b32 s24, 1
	s_mov_b64 s[14:15], 0
	v_mov_b32_e32 v1, 0
	s_branch .LBB0_780
